# plus: gate/up GEMM epilogue issues its four rstd loads together instead of four load+vmcnt(0) round trips
# speedup vs baseline: 1.2794x; 1.0048x over previous
; DEVINL float lane_xor1(float v) { return dpp_f<0xB1>(v); }
; DEVINL int ridx(int r) { return ((r >> 4) << 5) | (r & 15); }
; DEVINL void store_pairs(u16* base, size_t ld, int rb, int col, float v0, float v1, float v2, float v3) {
;   const float p0 = lane_xor1(v0), p1 = lane_xor1(v1), p2 = lane_xor1(v2), p3 = lane_xor1(v3);
;   const bool odd = (col & 1) != 0;
;   const int r0 = odd ? rb + 2 : rb, c0 = col & ~1;
;   const unsigned w0 = odd ? pack2(p2, v2) : pack2(v0, p0);
;   const unsigned w1 = odd ? pack2(p3, v3) : pack2(v1, p1);
;   *(unsigned*)(base + (size_t)r0 * ld + c0) = w0;
;   *(unsigned*)(base + (size_t)(r0 + 1) * ld + c0) = w1;
; }
; DEVINL float sigmoidf_(float x) { return __builtin_amdgcn_rcpf(1.f + __expf(-x)); }
; DEVINL float siluf_(float x) { return x * __builtin_amdgcn_rcpf(1.f + __expf(-x)); }
; DEVINL void p6_tile(const Params& p, char* smem, int mt, int nt) {
;     ...
;   for (int mf = 0; mf < 4; ++mf) {
;     const int rb = m0 + wr * 64 + mf * 16 + (lane >> 4) * 4;
;     float rs[4];
; #pragma unroll
;     for (int j = 0; j < 4; ++j) rs[j] = rstd1[ridx(rb) + j];
; #pragma unroll
;     for (int nf = 0; nf < 2; ++nf) {
;       const int hid = nt * 64 + wc * 32 + nf * 16 + (lane & 15);
;       float a[4];
; #pragma unroll
;       for (int j = 0; j < 4; ++j) {
;         float g = acc[mf][nf][j] * rs[j], u = acc[mf][nf + 2][j] * rs[j];
;         a[j] = siluf_(g) * u;
;       }
;       store_pairs(actb, DFF, rb, hid, a[0], a[1], a[2], a[3]);
;     }
.Ldt_b116_tail:
	s_waitcnt vmcnt(0)
	s_barrier
	s_waitcnt lgkmcnt(9)
	v_mov_b32_e32 v176, v52
	v_mov_b32_e32 v177, v53
	v_mov_b32_e32 v178, v54
	v_mov_b32_e32 v179, v55
	v_readlane_b32 s40, v194, 13
	v_readlane_b32 s41, v194, 14
	v_add_u32_e32 v3, v3, v1
	v_mov_b32_e32 v52, v36
	v_mov_b32_e32 v53, v37
	v_mov_b32_e32 v54, v38
	v_mov_b32_e32 v55, v39
	s_waitcnt lgkmcnt(8)
	v_mov_b32_e32 v36, v28
	v_mov_b32_e32 v37, v29
	v_mov_b32_e32 v38, v30
	v_mov_b32_e32 v39, v31
	s_nop 2
	v_mov_b32_e32 v28, v0
	v_mov_b32_e32 v29, v0
	v_mov_b32_e32 v168, v64
	v_mov_b32_e32 v169, v65
	v_mov_b32_e32 v170, v66
	v_mov_b32_e32 v171, v67
	v_lshlrev_b32_e32 v30, 6, v102
	v_mov_b32_e32 v64, v24
	v_mov_b32_e32 v65, v25
	v_mov_b32_e32 v66, v26
	v_mov_b32_e32 v67, v27
	v_and_b32_e32 v31, 14, v28
	s_nop 1
	v_ashrrev_i32_e32 v24, 1, v29
	v_mov_b32_e32 v184, v44
	v_mov_b32_e32 v185, v45
	v_mov_b32_e32 v186, v46
	v_mov_b32_e32 v187, v47
	v_and_b32_e32 v24, 0xffffffc0, v24
	v_add_u32_e32 v105, v24, v105
	v_lshrrev_b32_e32 v29, 1, v29
	v_mov_b32_e32 v44, v20
	v_mov_b32_e32 v45, v21
	v_mov_b32_e32 v46, v22
	v_mov_b32_e32 v47, v23
	v_and_b32_e32 v29, 32, v29
	s_nop 1
	v_lshrrev_b32_e32 v20, 2, v28
	v_and_b32_e32 v131, 12, v20
	v_mov_b32_e32 v20, v12
	v_mov_b32_e32 v21, v13
	v_mov_b32_e32 v22, v14
	v_mov_b32_e32 v23, v15
	s_nop 2
	v_lshl_or_b32 v12, v105, 1, v131
	v_ashrrev_i32_e32 v13, 31, v12
	v_lshl_add_u64 v[24:25], v[12:13], 2, s[40:41]
	v_mov_b32_e32 v12, v32
	v_mov_b32_e32 v13, v33
	v_mov_b32_e32 v14, v34
	v_mov_b32_e32 v15, v35
	s_nop 2
	global_load_dwordx4 v[32:35], v[24:25], off
	global_load_dwordx4 v[144:147], v[24:25], off offset:128
	global_load_dwordx4 v[148:151], v[24:25], off offset:256
	global_load_dwordx4 v[152:155], v[24:25], off offset:384
	v_mov_b32_e32 v164, v68
	v_mov_b32_e32 v165, v69
	v_mov_b32_e32 v166, v70
	v_mov_b32_e32 v167, v71
	v_mov_b64_e32 v[108:109], s[84:85]
	s_waitcnt lgkmcnt(5)
	v_mov_b32_e32 v24, v76
	v_mov_b32_e32 v25, v77
	v_mov_b32_e32 v26, v78
	v_mov_b32_e32 v27, v79
	s_waitcnt lgkmcnt(4)
	v_mov_b32_e32 v68, v72
	v_mov_b32_e32 v69, v73
	v_mov_b32_e32 v70, v74
	v_mov_b32_e32 v71, v75
	s_nop 2
	v_and_b32_e32 v72, 1, v28
	v_lshl_or_b32 v102, v72, 1, v131
	v_mov_b32_e32 v172, v56
	v_mov_b32_e32 v173, v57
	v_mov_b32_e32 v174, v58
	v_mov_b32_e32 v175, v59
	v_or3_b32 v28, v29, v30, v31
	v_cmp_eq_u32_e32 vcc, 0, v72
	v_ashrrev_i32_e32 v29, 31, v28
	v_or_b32_e32 v56, v105, v102
	v_or_b32_e32 v73, 1, v56
	v_mad_i64_i32 v[30:31], s[38:39], v56, s24, v[108:109]
	v_mov_b32_e32 v56, v60
	v_mov_b32_e32 v57, v61
	v_mov_b32_e32 v58, v62
	v_mov_b32_e32 v59, v63
	v_lshlrev_b64 v[106:107], 1, v[28:29]
	s_waitcnt vmcnt(0)
	v_mul_f32_e32 v75, v25, v33
	v_mad_i64_i32 v[60:61], s[38:39], v73, s24, v[108:109]
	v_mul_f32_e32 v73, v24, v32
	v_mul_f32_e32 v133, v26, v34
	v_mul_f32_e32 v135, v27, v35
	v_mul_f32_e32 v24, 0xbfb8aa3b, v73
	v_mul_f32_e32 v25, 0xbfb8aa3b, v75
	v_mul_f32_e32 v26, 0xbfb8aa3b, v133
	v_mul_f32_e32 v27, 0xbfb8aa3b, v135
	v_exp_f32_e32 v24, v24
	v_exp_f32_e32 v25, v25
	v_exp_f32_e32 v26, v26
	v_exp_f32_e32 v27, v27
	v_add_f32_e32 v24, 1.0, v24
	v_add_f32_e32 v25, 1.0, v25
	v_add_f32_e32 v26, 1.0, v26
	v_add_f32_e32 v27, 1.0, v27
	v_mov_b32_e32 v180, v48
	v_mov_b32_e32 v181, v49
	v_mov_b32_e32 v182, v50
	v_mov_b32_e32 v183, v51
	v_lshl_add_u64 v[110:111], v[30:31], 0, v[106:107]
	v_mul_f32_e32 v68, v68, v32
	v_lshl_add_u64 v[112:113], v[60:61], 0, v[106:107]
	v_mov_b32_e32 v48, v40
	v_mov_b32_e32 v49, v41
	v_mov_b32_e32 v50, v42
	v_mov_b32_e32 v51, v43
	v_rcp_f32_e32 v137, v24
	v_rcp_f32_e32 v138, v25
	v_rcp_f32_e32 v139, v26
	s_waitcnt lgkmcnt(1)
	v_mov_b32_e32 v40, v164
	v_mov_b32_e32 v41, v165
	v_mov_b32_e32 v42, v166
	v_mov_b32_e32 v43, v167
	v_rcp_f32_e32 v140, v27
	v_mul_f32_e32 v73, v73, v137
	v_mul_f32_e32 v75, v75, v138
	v_mul_f32_e32 v133, v133, v139
	v_mul_f32_e32 v135, v135, v140
	s_nop 2
	v_mul_f32_e32 v74, v40, v32
	v_mul_f32_e32 v132, v41, v33
	v_mul_f32_e32 v134, v42, v34
	v_mul_f32_e32 v136, v43, v35
	v_mul_f32_e32 v73, v74, v73
	v_mul_f32_e32 v74, v132, v75
	v_mul_f32_e32 v75, v134, v133
	v_mul_f32_e32 v132, v136, v135
	v_mov_b32_dpp v133, v73 quad_perm:[1,0,3,2] row_mask:0xf bank_mask:0xf bound_ctrl:1
	v_mov_b32_dpp v134, v74 quad_perm:[1,0,3,2] row_mask:0xf bank_mask:0xf bound_ctrl:1
	v_mov_b32_dpp v135, v75 quad_perm:[1,0,3,2] row_mask:0xf bank_mask:0xf bound_ctrl:1
	v_mov_b32_dpp v136, v132 quad_perm:[1,0,3,2] row_mask:0xf bank_mask:0xf bound_ctrl:1
	v_cndmask_b32_e32 v72, v75, v133, vcc
	v_cndmask_b32_e32 v73, v135, v73, vcc
	v_cndmask_b32_e32 v75, v132, v134, vcc
	v_cndmask_b32_e32 v74, v136, v74, vcc
	v_add_u32_e32 v72, 0x8000, v72
	v_add_u32_e32 v73, 0x8000, v73
	v_add_u32_e32 v75, 0x8000, v75
	v_add_u32_e32 v74, 0x8000, v74
	v_perm_b32 v72, v72, v73, s25
	v_perm_b32 v73, v75, v74, s25
	global_store_dword v[110:111], v72, off
	global_store_dword v[112:113], v73, off
	v_mov_b32_e32 v72, v52
	v_mov_b32_e32 v73, v53
	v_mov_b32_e32 v74, v54
	v_mov_b32_e32 v75, v55
	v_mul_f32_e32 v69, v69, v33
	s_nop 1
	v_mul_f32_e32 v52, 0xbfb8aa3b, v68
	v_exp_f32_e32 v132, v52
	s_waitcnt lgkmcnt(0)
; DEVINL float lane_xor1(float v) { return dpp_f<0xB1>(v); }
; DEVINL int ridx(int r) { return ((r >> 4) << 5) | (r & 15); }
; DEVINL void store_pairs(u16* base, size_t ld, int rb, int col, float v0, float v1, float v2, float v3) {
;   const float p0 = lane_xor1(v0), p1 = lane_xor1(v1), p2 = lane_xor1(v2), p3 = lane_xor1(v3);
;   const bool odd = (col & 1) != 0;
;   const int r0 = odd ? rb + 2 : rb, c0 = col & ~1;
;   const unsigned w0 = odd ? pack2(p2, v2) : pack2(v0, p0);
;   const unsigned w1 = odd ? pack2(p3, v3) : pack2(v1, p1);
;   *(unsigned*)(base + (size_t)r0 * ld + c0) = w0;
;   *(unsigned*)(base + (size_t)(r0 + 1) * ld + c0) = w1;
; }
; DEVINL float sigmoidf_(float x) { return __builtin_amdgcn_rcpf(1.f + __expf(-x)); }
; DEVINL float siluf_(float x) { return x * __builtin_amdgcn_rcpf(1.f + __expf(-x)); }
; DEVINL void p6_tile(const Params& p, char* smem, int mt, int nt) {
;     ...
;   for (int mf = 0; mf < 4; ++mf) {
;     const int rb = m0 + wr * 64 + mf * 16 + (lane >> 4) * 4;
;     float rs[4];
; #pragma unroll
;     for (int j = 0; j < 4; ++j) rs[j] = rstd1[ridx(rb) + j];
; #pragma unroll
;     for (int nf = 0; nf < 2; ++nf) {
;       const int hid = nt * 64 + wc * 32 + nf * 16 + (lane & 15);
;       float a[4];
; #pragma unroll
;       for (int j = 0; j < 4; ++j) {
;         float g = acc[mf][nf][j] * rs[j], u = acc[mf][nf + 2][j] * rs[j];
;         a[j] = siluf_(g) * u;
;       }
;       store_pairs(actb, DFF, rb, hid, a[0], a[1], a[2], a[3]);
;     }
	v_mov_b32_e32 v52, v36
	v_mov_b32_e32 v53, v37
	v_mov_b32_e32 v54, v38
	v_mov_b32_e32 v55, v39
	s_nop 2
	v_mul_f32_e32 v36, 0xbfb8aa3b, v69
	v_mov_b32_e32 v24, v184
	v_mov_b32_e32 v25, v185
	v_mov_b32_e32 v26, v186
	v_mov_b32_e32 v27, v187
	v_exp_f32_e32 v88, v36
	v_mov_b32_e32 v36, v64
	v_mov_b32_e32 v37, v65
	v_mov_b32_e32 v38, v66
	v_mov_b32_e32 v39, v67
	s_nop 2
	v_add_f32_e32 v64, 1.0, v132
	v_mov_b32_e32 v76, v168
	v_mov_b32_e32 v77, v169
	v_mov_b32_e32 v78, v170
	v_mov_b32_e32 v79, v171
	v_rcp_f32_e32 v64, v64
	v_add_f32_e32 v65, 1.0, v88
	v_rcp_f32_e32 v65, v65
	v_mul_f32_e32 v66, v71, v35
	v_mul_f32_e32 v64, v68, v64
	s_nop 2
	v_mul_f32_e32 v32, v76, v32
	v_mul_f32_e32 v32, v32, v64
	v_mul_f32_e32 v33, v77, v33
	v_mul_f32_e32 v64, v69, v65
	v_mul_f32_e32 v33, v33, v64
	v_mul_f32_e32 v64, v70, v34
	v_mul_f32_e32 v65, 0xbfb8aa3b, v64
	v_exp_f32_e32 v65, v65
	v_mul_f32_e32 v67, 0xbfb8aa3b, v66
	v_exp_f32_e32 v67, v67
	v_mul_f32_e32 v34, v78, v34
	v_add_f32_e32 v65, 1.0, v65
	v_rcp_f32_e32 v65, v65
	v_add_f32_e32 v67, 1.0, v67
	v_rcp_f32_e32 v67, v67
	v_mul_f32_e32 v35, v79, v35
	v_mul_f32_e32 v64, v64, v65
	v_mul_f32_e32 v34, v34, v64
	v_mul_f32_e32 v64, v66, v67
	v_mul_f32_e32 v35, v35, v64
	v_mov_b32_dpp v66, v34 quad_perm:[1,0,3,2] row_mask:0xf bank_mask:0xf bound_ctrl:1
	v_mov_b32_dpp v64, v32 quad_perm:[1,0,3,2] row_mask:0xf bank_mask:0xf bound_ctrl:1
	v_cndmask_b32_e32 v34, v34, v64, vcc
	v_cndmask_b32_e32 v32, v66, v32, vcc
	v_mov_b32_dpp v65, v33 quad_perm:[1,0,3,2] row_mask:0xf bank_mask:0xf bound_ctrl:1
	v_mov_b32_dpp v67, v35 quad_perm:[1,0,3,2] row_mask:0xf bank_mask:0xf bound_ctrl:1
	v_add_u32_e32 v34, 0x8000, v34
	v_add_u32_e32 v32, 0x8000, v32
	v_perm_b32 v32, v34, v32, s25
	v_cndmask_b32_e32 v34, v35, v65, vcc
	v_cndmask_b32_e32 v33, v67, v33, vcc
	v_add_u32_e32 v34, 0x8000, v34
	v_add_u32_e32 v33, 0x8000, v33
	v_or_b32_e32 v68, 16, v105
	v_perm_b32 v33, v34, v33, s25
	global_store_dword v[110:111], v32, off offset:32
	global_store_dword v[112:113], v33, off offset:32
	v_lshl_or_b32 v32, v68, 1, v131
	v_ashrrev_i32_e32 v33, 31, v32
	v_lshl_add_u64 v[32:33], v[32:33], 2, s[40:41]
	v_mov_b32_e32 v64, v144
	v_mov_b32_e32 v65, v145
	v_mov_b32_e32 v66, v146
	v_mov_b32_e32 v67, v147
	v_mov_b32_e32 v60, v176
	v_mov_b32_e32 v61, v177
	v_mov_b32_e32 v62, v178
	v_mov_b32_e32 v63, v179
	v_mov_b32_e32 v32, v44
	v_mov_b32_e32 v33, v45
	v_mov_b32_e32 v34, v46
	v_mov_b32_e32 v35, v47
	s_nop 2
	v_or_b32_e32 v44, v68, v102
	v_mad_i64_i32 v[68:69], s[38:39], v44, s24, v[108:109]
	v_or_b32_e32 v44, 1, v44
	v_mad_i64_i32 v[70:71], s[38:39], v44, s24, v[108:109]
	v_mov_b32_e32 v28, v172
	v_mov_b32_e32 v29, v173
	v_mov_b32_e32 v30, v174
	v_mov_b32_e32 v31, v175
	v_mov_b32_e32 v44, v65
	v_mov_b32_e32 v45, v66
	v_mul_f32_e32 v47, v56, v64
	v_mul_f32_e32 v56, v60, v64
	v_mul_f32_e32 v60, 0xbfb8aa3b, v47
	v_mul_f32_e32 v57, v57, v44
	v_mul_f32_e32 v58, v58, v45
	v_mov_b32_e32 v46, v67
	v_exp_f32_e32 v60, v60
	v_mul_f32_e32 v65, 0xbfb8aa3b, v57
	v_mul_f32_e32 v66, 0xbfb8aa3b, v58
	v_mul_f32_e32 v59, v59, v46
	v_exp_f32_e32 v65, v65
	v_exp_f32_e32 v66, v66
	v_mul_f32_e32 v67, 0xbfb8aa3b, v59
	v_exp_f32_e32 v67, v67
	v_add_f32_e32 v60, 1.0, v60
	v_rcp_f32_e32 v60, v60
	v_add_f32_e32 v65, 1.0, v65
	v_add_f32_e32 v66, 1.0, v66
	v_rcp_f32_e32 v65, v65
	v_rcp_f32_e32 v66, v66
	v_add_f32_e32 v67, 1.0, v67
	v_rcp_f32_e32 v67, v67
	v_mul_f32_e32 v47, v47, v60
	v_mul_f32_e32 v62, v62, v45
	v_mul_f32_e32 v47, v56, v47
	v_mul_f32_e32 v56, v57, v65
	v_mul_f32_e32 v57, v58, v66
	v_mul_f32_e32 v61, v61, v44
	v_mul_f32_e32 v57, v62, v57
	v_mul_f32_e32 v63, v63, v46
	v_mul_f32_e32 v56, v61, v56
	v_mul_f32_e32 v58, v59, v67
	v_mov_b32_dpp v59, v47 quad_perm:[1,0,3,2] row_mask:0xf bank_mask:0xf bound_ctrl:1
	v_mov_b32_dpp v61, v57 quad_perm:[1,0,3,2] row_mask:0xf bank_mask:0xf bound_ctrl:1
	v_mul_f32_e32 v58, v63, v58
	v_cndmask_b32_e32 v57, v57, v59, vcc
	v_cndmask_b32_e32 v47, v61, v47, vcc
	v_mov_b32_dpp v60, v56 quad_perm:[1,0,3,2] row_mask:0xf bank_mask:0xf bound_ctrl:1
	v_mov_b32_dpp v62, v58 quad_perm:[1,0,3,2] row_mask:0xf bank_mask:0xf bound_ctrl:1
	v_add_u32_e32 v57, 0x8000, v57
	v_add_u32_e32 v47, 0x8000, v47
	v_perm_b32 v47, v57, v47, s25
	v_cndmask_b32_e32 v57, v58, v60, vcc
	v_cndmask_b32_e32 v56, v62, v56, vcc
	v_add_u32_e32 v57, 0x8000, v57
	v_add_u32_e32 v56, 0x8000, v56
	v_perm_b32 v60, v57, v56, s25
	v_lshl_add_u64 v[56:57], v[68:69], 0, v[106:107]
	v_mul_f32_e32 v28, v28, v64
	global_store_dword v[56:57], v47, off
	v_lshl_add_u64 v[58:59], v[70:71], 0, v[106:107]
	v_mul_f32_e32 v47, 0xbfb8aa3b, v28
	v_mul_f32_e32 v29, v29, v44
	global_store_dword v[58:59], v60, off
	v_exp_f32_e32 v47, v47
	v_mul_f32_e32 v60, 0xbfb8aa3b, v29
	v_exp_f32_e32 v60, v60
	v_mov_b32_e32 v40, v180
	v_mov_b32_e32 v41, v181
	v_mov_b32_e32 v42, v182
	v_mov_b32_e32 v43, v183
	v_add_f32_e32 v47, 1.0, v47
	v_rcp_f32_e32 v47, v47
	v_add_f32_e32 v60, 1.0, v60
	v_rcp_f32_e32 v60, v60
	v_mul_f32_e32 v30, v30, v45
	s_nop 2
	v_mul_f32_e32 v40, v40, v64
	v_mul_f32_e32 v28, v28, v47
	v_mul_f32_e32 v28, v40, v28
	v_mul_f32_e32 v40, v41, v44
	v_mul_f32_e32 v29, v29, v60
	v_mul_f32_e32 v29, v40, v29
	v_mul_f32_e32 v40, 0xbfb8aa3b, v30
	v_mul_f32_e32 v31, v31, v46
	v_exp_f32_e32 v40, v40
	v_mul_f32_e32 v41, 0xbfb8aa3b, v31
	v_exp_f32_e32 v41, v41
	v_mul_f32_e32 v42, v42, v45
	v_add_f32_e32 v40, 1.0, v40
	v_rcp_f32_e32 v40, v40
	v_add_f32_e32 v41, 1.0, v41
	v_rcp_f32_e32 v41, v41
	v_mov_b32_e32 v16, v20
	v_mov_b32_e32 v17, v21
	v_mov_b32_e32 v18, v22
	v_mov_b32_e32 v19, v23
	v_mul_f32_e32 v30, v30, v40
	v_mul_f32_e32 v30, v42, v30
	v_mul_f32_e32 v40, v43, v46
	v_mul_f32_e32 v31, v31, v41
; DEVINL float lane_xor1(float v) { return dpp_f<0xB1>(v); }
; DEVINL int ridx(int r) { return ((r >> 4) << 5) | (r & 15); }
; DEVINL void store_pairs(u16* base, size_t ld, int rb, int col, float v0, float v1, float v2, float v3) {
;   const float p0 = lane_xor1(v0), p1 = lane_xor1(v1), p2 = lane_xor1(v2), p3 = lane_xor1(v3);
;   const bool odd = (col & 1) != 0;
;   const int r0 = odd ? rb + 2 : rb, c0 = col & ~1;
;   const unsigned w0 = odd ? pack2(p2, v2) : pack2(v0, p0);
;   const unsigned w1 = odd ? pack2(p3, v3) : pack2(v1, p1);
;   *(unsigned*)(base + (size_t)r0 * ld + c0) = w0;
;   *(unsigned*)(base + (size_t)(r0 + 1) * ld + c0) = w1;
; }
; DEVINL float sigmoidf_(float x) { return __builtin_amdgcn_rcpf(1.f + __expf(-x)); }
; DEVINL float siluf_(float x) { return x * __builtin_amdgcn_rcpf(1.f + __expf(-x)); }
; DEVINL void p6_tile(const Params& p, char* smem, int mt, int nt) {
;     ...
;   for (int mf = 0; mf < 4; ++mf) {
;     const int rb = m0 + wr * 64 + mf * 16 + (lane >> 4) * 4;
;     float rs[4];
; #pragma unroll
;     for (int j = 0; j < 4; ++j) rs[j] = rstd1[ridx(rb) + j];
; #pragma unroll
;     for (int nf = 0; nf < 2; ++nf) {
;       const int hid = nt * 64 + wc * 32 + nf * 16 + (lane & 15);
;       float a[4];
; #pragma unroll
;       for (int j = 0; j < 4; ++j) {
;         float g = acc[mf][nf][j] * rs[j], u = acc[mf][nf + 2][j] * rs[j];
;         a[j] = siluf_(g) * u;
;       }
;       store_pairs(actb, DFF, rb, hid, a[0], a[1], a[2], a[3]);
;     }
	v_mul_f32_e32 v31, v40, v31
	v_mov_b32_dpp v40, v28 quad_perm:[1,0,3,2] row_mask:0xf bank_mask:0xf bound_ctrl:1
	v_mov_b32_dpp v42, v30 quad_perm:[1,0,3,2] row_mask:0xf bank_mask:0xf bound_ctrl:1
	v_cndmask_b32_e32 v30, v30, v40, vcc
	v_cndmask_b32_e32 v28, v42, v28, vcc
	v_mov_b32_dpp v41, v29 quad_perm:[1,0,3,2] row_mask:0xf bank_mask:0xf bound_ctrl:1
	v_mov_b32_dpp v43, v31 quad_perm:[1,0,3,2] row_mask:0xf bank_mask:0xf bound_ctrl:1
	v_add_u32_e32 v30, 0x8000, v30
	v_add_u32_e32 v28, 0x8000, v28
	v_perm_b32 v28, v30, v28, s25
	v_cndmask_b32_e32 v30, v31, v41, vcc
	v_cndmask_b32_e32 v29, v43, v29, vcc
	v_add_u32_e32 v30, 0x8000, v30
	v_add_u32_e32 v29, 0x8000, v29
	v_or_b32_e32 v40, 32, v105
	v_perm_b32 v29, v30, v29, s25
	global_store_dword v[56:57], v28, off offset:32
	global_store_dword v[58:59], v29, off offset:32
	v_lshl_or_b32 v28, v40, 1, v131
	v_ashrrev_i32_e32 v29, 31, v28
	v_lshl_add_u64 v[28:29], v[28:29], 2, s[40:41]
	v_mov_b32_e32 v28, v148
	v_mov_b32_e32 v29, v149
	v_mov_b32_e32 v30, v150
	v_mov_b32_e32 v31, v151
	v_or_b32_e32 v20, v40, v102
	v_mad_i64_i32 v[40:41], s[38:39], v20, s24, v[108:109]
	v_or_b32_e32 v20, 1, v20
	v_mad_i64_i32 v[42:43], s[38:39], v20, s24, v[108:109]
	v_mov_b32_e32 v4, v12
	v_mov_b32_e32 v5, v13
	v_mov_b32_e32 v6, v14
	v_mov_b32_e32 v7, v15
	v_mov_b32_e32 v20, v29
	v_mul_f32_e32 v23, v24, v28
	v_mov_b32_e32 v21, v30
	v_mov_b32_e32 v22, v31
	v_mul_f32_e32 v29, 0xbfb8aa3b, v23
	v_mul_f32_e32 v25, v25, v20
	v_exp_f32_e32 v29, v29
	v_mul_f32_e32 v31, 0xbfb8aa3b, v25
	v_exp_f32_e32 v31, v31
	v_mul_f32_e32 v26, v26, v21
	v_add_f32_e32 v29, 1.0, v29
	v_rcp_f32_e32 v29, v29
	v_add_f32_e32 v31, 1.0, v31
	v_rcp_f32_e32 v31, v31
	v_mul_f32_e32 v24, v72, v28
	v_mul_f32_e32 v44, 0xbfb8aa3b, v26
	v_mul_f32_e32 v23, v23, v29
	v_mul_f32_e32 v27, v27, v22
	v_mul_f32_e32 v23, v24, v23
	v_mul_f32_e32 v24, v25, v31
	v_exp_f32_e32 v25, v44
	v_mul_f32_e32 v29, 0xbfb8aa3b, v27
	v_exp_f32_e32 v29, v29
	v_mul_f32_e32 v30, v73, v20
	v_add_f32_e32 v25, 1.0, v25
	v_rcp_f32_e32 v25, v25
	v_add_f32_e32 v29, 1.0, v29
	v_rcp_f32_e32 v29, v29
	v_mul_f32_e32 v24, v30, v24
	v_mul_f32_e32 v30, v74, v21
	v_mul_f32_e32 v25, v26, v25
	v_mul_f32_e32 v25, v30, v25
	v_mul_f32_e32 v26, v75, v22
	v_mul_f32_e32 v27, v27, v29
	v_mul_f32_e32 v26, v26, v27
	v_mov_b32_dpp v30, v25 quad_perm:[1,0,3,2] row_mask:0xf bank_mask:0xf bound_ctrl:1
	v_mov_b32_dpp v27, v23 quad_perm:[1,0,3,2] row_mask:0xf bank_mask:0xf bound_ctrl:1
	v_cndmask_b32_e32 v25, v25, v27, vcc
	v_cndmask_b32_e32 v23, v30, v23, vcc
	v_mov_b32_dpp v29, v24 quad_perm:[1,0,3,2] row_mask:0xf bank_mask:0xf bound_ctrl:1
	v_mov_b32_dpp v31, v26 quad_perm:[1,0,3,2] row_mask:0xf bank_mask:0xf bound_ctrl:1
	v_add_u32_e32 v25, 0x8000, v25
	v_add_u32_e32 v23, 0x8000, v23
	v_perm_b32 v23, v25, v23, s25
	v_cndmask_b32_e32 v25, v26, v29, vcc
	v_cndmask_b32_e32 v24, v31, v24, vcc
	v_add_u32_e32 v25, 0x8000, v25
	v_add_u32_e32 v24, 0x8000, v24
	v_perm_b32 v29, v25, v24, s25
	v_lshl_add_u64 v[24:25], v[40:41], 0, v[106:107]
	global_store_dword v[24:25], v23, off
	v_lshl_add_u64 v[26:27], v[42:43], 0, v[106:107]
	v_mul_f32_e32 v23, v48, v28
	global_store_dword v[26:27], v29, off
	v_mul_f32_e32 v29, 0xbfb8aa3b, v23
	v_mul_f32_e32 v30, v49, v20
	v_exp_f32_e32 v29, v29
	v_mul_f32_e32 v31, 0xbfb8aa3b, v30
	v_exp_f32_e32 v31, v31
	v_mul_f32_e32 v28, v52, v28
	v_add_f32_e32 v29, 1.0, v29
	v_rcp_f32_e32 v29, v29
	v_add_f32_e32 v31, 1.0, v31
	v_rcp_f32_e32 v31, v31
	v_mul_f32_e32 v20, v53, v20
	v_mul_f32_e32 v23, v23, v29
	v_mul_f32_e32 v23, v28, v23
	v_mul_f32_e32 v28, v30, v31
	v_mul_f32_e32 v20, v20, v28
	v_mul_f32_e32 v28, v50, v21
	v_mul_f32_e32 v29, 0xbfb8aa3b, v28
	v_mul_f32_e32 v30, v51, v22
	v_exp_f32_e32 v29, v29
	v_mul_f32_e32 v31, 0xbfb8aa3b, v30
	v_exp_f32_e32 v31, v31
	v_mul_f32_e32 v21, v54, v21
	v_add_f32_e32 v29, 1.0, v29
	v_rcp_f32_e32 v29, v29
	v_add_f32_e32 v31, 1.0, v31
	v_rcp_f32_e32 v31, v31
	v_mul_f32_e32 v22, v55, v22
	v_mul_f32_e32 v28, v28, v29
	v_mul_f32_e32 v21, v21, v28
	v_mul_f32_e32 v28, v30, v31
	v_mul_f32_e32 v22, v22, v28
	v_mov_b32_dpp v30, v21 quad_perm:[1,0,3,2] row_mask:0xf bank_mask:0xf bound_ctrl:1
	v_mov_b32_dpp v28, v23 quad_perm:[1,0,3,2] row_mask:0xf bank_mask:0xf bound_ctrl:1
	v_mov_b32_dpp v29, v20 quad_perm:[1,0,3,2] row_mask:0xf bank_mask:0xf bound_ctrl:1
	v_mov_b32_dpp v31, v22 quad_perm:[1,0,3,2] row_mask:0xf bank_mask:0xf bound_ctrl:1
	v_cndmask_b32_e32 v21, v21, v28, vcc
; DEVINL float siluf_(float x) { return x * __builtin_amdgcn_rcpf(1.f + __expf(-x)); }
; DEVINL int ridx(int r) { return ((r >> 4) << 5) | (r & 15); }
; DEVINL void p6_tile(const Params& p, char* smem, int mt, int nt) {
;     ...
;   for (int mf = 0; mf < 4; ++mf) {
;     const int rb = m0 + wr * 64 + mf * 16 + (lane >> 4) * 4;
;     float rs[4];
; #pragma unroll
;     for (int j = 0; j < 4; ++j) rs[j] = rstd1[ridx(rb) + j];
; #pragma unroll
;     for (int nf = 0; nf < 2; ++nf) {
;       const int hid = nt * 64 + wc * 32 + nf * 16 + (lane & 15);
;       float a[4];
; #pragma unroll
;       for (int j = 0; j < 4; ++j) {
;         float g = acc[mf][nf][j] * rs[j], u = acc[mf][nf + 2][j] * rs[j];
;         a[j] = siluf_(g) * u;
;       }
;       store_pairs(actb, DFF, rb, hid, a[0], a[1], a[2], a[3]);
;     }
; template <class F>
; DEVINL void gemm_phase(int NT, F&& f) {
;     ...
;   for (int u = u0 + j; u < u1; u += nbx) {
;     const int band = u / (8 * MT), v = u - band * 8 * MT;
;     const int w = min(8, NT - band * 8);
;     f(v / w, band * 8 + v % w);
	v_cndmask_b32_e32 v23, v30, v23, vcc
	v_add_u32_e32 v21, 0x8000, v21
	v_add_u32_e32 v23, 0x8000, v23
	v_cndmask_b32_e32 v22, v22, v29, vcc
	v_cndmask_b32_e32 v20, v31, v20, vcc
	v_perm_b32 v21, v21, v23, s25
	v_add_u32_e32 v22, 0x8000, v22
	v_add_u32_e32 v20, 0x8000, v20
	v_perm_b32 v20, v22, v20, s25
	global_store_dword v[24:25], v21, off offset:32
	global_store_dword v[26:27], v20, off offset:32
	v_or_b32_e32 v24, 48, v105
	v_lshl_or_b32 v20, v24, 1, v131
	v_ashrrev_i32_e32 v21, 31, v20
	v_lshl_add_u64 v[20:21], v[20:21], 2, s[40:41]
	v_mov_b32_e32 v20, v152
	v_mov_b32_e32 v21, v153
	v_mov_b32_e32 v22, v154
	v_mov_b32_e32 v23, v155
	v_or_b32_e32 v11, v24, v102
	v_mad_i64_i32 v[12:13], s[38:39], v11, s24, v[108:109]
	v_or_b32_e32 v11, 1, v11
	v_mad_i64_i32 v[14:15], s[38:39], v11, s24, v[108:109]
	v_lshl_add_u64 v[12:13], v[12:13], 0, v[106:107]
	v_lshl_add_u64 v[14:15], v[14:15], 0, v[106:107]
	v_mov_b32_e32 v8, v21
	v_mul_f32_e32 v11, v36, v20
	v_mov_b32_e32 v9, v22
	v_mov_b32_e32 v10, v23
	v_mul_f32_e32 v21, 0xbfb8aa3b, v11
	v_mul_f32_e32 v22, v37, v8
	v_exp_f32_e32 v21, v21
	v_mul_f32_e32 v23, 0xbfb8aa3b, v22
	v_exp_f32_e32 v23, v23
	v_mul_f32_e32 v16, v16, v20
	v_add_f32_e32 v21, 1.0, v21
	v_rcp_f32_e32 v21, v21
	v_add_f32_e32 v23, 1.0, v23
	v_rcp_f32_e32 v23, v23
	v_mul_f32_e32 v18, v18, v9
	v_mul_f32_e32 v11, v11, v21
	v_mul_f32_e32 v11, v16, v11
	v_mul_f32_e32 v16, v17, v8
	v_mul_f32_e32 v17, v22, v23
	v_mul_f32_e32 v16, v16, v17
	v_mul_f32_e32 v17, v38, v9
	v_mul_f32_e32 v21, 0xbfb8aa3b, v17
	v_mul_f32_e32 v22, v39, v10
	v_exp_f32_e32 v21, v21
	v_mul_f32_e32 v23, 0xbfb8aa3b, v22
	v_exp_f32_e32 v23, v23
	v_mul_f32_e32 v5, v5, v8
	v_add_f32_e32 v21, 1.0, v21
	v_rcp_f32_e32 v21, v21
	v_add_f32_e32 v23, 1.0, v23
	v_rcp_f32_e32 v23, v23
	v_mul_f32_e32 v4, v4, v20
	v_mul_f32_e32 v17, v17, v21
	v_mul_f32_e32 v17, v18, v17
	v_mul_f32_e32 v18, v19, v10
	v_mul_f32_e32 v19, v22, v23
	v_mul_f32_e32 v18, v18, v19
	v_mov_b32_dpp v22, v17 quad_perm:[1,0,3,2] row_mask:0xf bank_mask:0xf bound_ctrl:1
	v_mov_b32_dpp v19, v11 quad_perm:[1,0,3,2] row_mask:0xf bank_mask:0xf bound_ctrl:1
	v_cndmask_b32_e32 v17, v17, v19, vcc
	v_cndmask_b32_e32 v11, v22, v11, vcc
	v_mov_b32_dpp v21, v16 quad_perm:[1,0,3,2] row_mask:0xf bank_mask:0xf bound_ctrl:1
	v_mov_b32_dpp v23, v18 quad_perm:[1,0,3,2] row_mask:0xf bank_mask:0xf bound_ctrl:1
	v_add_u32_e32 v17, 0x8000, v17
	v_add_u32_e32 v11, 0x8000, v11
	v_perm_b32 v11, v17, v11, s25
	v_cndmask_b32_e32 v17, v18, v21, vcc
	v_cndmask_b32_e32 v16, v23, v16, vcc
	v_add_u32_e32 v17, 0x8000, v17
	v_add_u32_e32 v16, 0x8000, v16
	v_perm_b32 v16, v17, v16, s25
	v_mul_f32_e32 v17, v33, v8
	global_store_dword v[12:13], v11, off
	v_mul_f32_e32 v11, v32, v20
	v_mul_f32_e32 v18, 0xbfb8aa3b, v17
	global_store_dword v[14:15], v16, off
	v_mul_f32_e32 v16, 0xbfb8aa3b, v11
	v_exp_f32_e32 v18, v18
	v_exp_f32_e32 v16, v16
	v_mul_f32_e32 v6, v6, v9
	v_mul_f32_e32 v7, v7, v10
	v_add_f32_e32 v18, 1.0, v18
	v_add_f32_e32 v16, 1.0, v16
	v_rcp_f32_e32 v18, v18
	v_rcp_f32_e32 v16, v16
	v_mul_f32_e32 v8, v17, v18
	v_mul_f32_e32 v11, v11, v16
	v_mul_f32_e32 v5, v5, v8
	v_mul_f32_e32 v8, v34, v9
	v_mul_f32_e32 v4, v4, v11
	v_mul_f32_e32 v11, 0xbfb8aa3b, v8
	v_mul_f32_e32 v16, v35, v10
	v_exp_f32_e32 v11, v11
	v_mul_f32_e32 v17, 0xbfb8aa3b, v16
	v_exp_f32_e32 v17, v17
	v_add_f32_e32 v11, 1.0, v11
	v_rcp_f32_e32 v11, v11
	v_add_f32_e32 v9, 1.0, v17
	v_rcp_f32_e32 v9, v9
	v_mul_f32_e32 v8, v8, v11
	v_mul_f32_e32 v6, v6, v8
	v_mul_f32_e32 v8, v16, v9
	v_mul_f32_e32 v7, v7, v8
	v_mov_b32_dpp v10, v6 quad_perm:[1,0,3,2] row_mask:0xf bank_mask:0xf bound_ctrl:1
	v_mov_b32_dpp v8, v4 quad_perm:[1,0,3,2] row_mask:0xf bank_mask:0xf bound_ctrl:1
	v_cndmask_b32_e32 v6, v6, v8, vcc
	v_cndmask_b32_e32 v4, v10, v4, vcc
	v_mov_b32_dpp v9, v5 quad_perm:[1,0,3,2] row_mask:0xf bank_mask:0xf bound_ctrl:1
	v_mov_b32_dpp v11, v7 quad_perm:[1,0,3,2] row_mask:0xf bank_mask:0xf bound_ctrl:1
	v_add_u32_e32 v6, 0x8000, v6
	v_add_u32_e32 v4, 0x8000, v4
	v_perm_b32 v4, v6, v4, s25
	v_cndmask_b32_e32 v6, v7, v9, vcc
	v_cndmask_b32_e32 v5, v11, v5, vcc
	v_add_u32_e32 v6, 0x8000, v6
	v_add_u32_e32 v5, 0x8000, v5
	v_cmp_le_i32_e32 vcc, s0, v3
	v_perm_b32 v5, v6, v5, s25
	s_or_b64 s[36:37], vcc, s[36:37]
	global_store_dword v[12:13], v4, off offset:32
	global_store_dword v[14:15], v5, off offset:32
	s_cmp_eq_u32 s101, 0
	s_cbranch_scc0 .Ldt_b116_latch2
	s_mov_b32 s101, 1
	v_subrev_u32_e32 v3, 127, v3
	s_branch .LBB0_115
